# speedup vs baseline: 1.0106x; 1.0039x over previous
; #define LAS __attribute__((address_space(3)))
; __global__ void __launch_bounds__(512, 2) fwd_megakernel(mk::Params p) {
;     ...
;     if (tid < 64) ((LAS unsigned*)(lds + 131072))[tid] = 0u;
;     __syncthreads();
;     (void)xcd_barrier_post((unsigned*)ws, (volatile LAS unsigned*)(lds + 131072 + 32));
;     grid.sync();
.LBB0_7:
	s_or_b64 exec, exec, s[6:7]
	v_lshrrev_b32_e32 v1, 20, v0
	v_lshrrev_b32_e32 v0, 10, v0
	v_or_b32_e32 v0, v0, v1
	s_movk_i32 s0, 0x3ff
	v_and_or_b32 v0, v0, s0, v254
	v_cmp_eq_u32_e32 vcc, 0, v0
	s_barrier
	s_mov_b64 s[6:7], exec
